# prompt band attention loop: second K fragment batch read at the loop top with the first (spare registers), no LDS round trip between the QK MFMA halves
# speedup vs baseline: 1.0001x; 1.0001x over previous
; #define LAS __attribute__((address_space(3)))
; template <bool DIFF, bool FIXED, bool F32SRC> ...
;     ...
;             const LAS unsigned char* kb = lds + buf * BUF; const LAS unsigned char* vb = kb + KBUF;
;             const int dqi = qloc - 64 * j - 4 * hi; const float dq = (float)dqi;
;             bf16x8 kf0[2], kf1[2];
; #pragma unroll
;             for (int ks = 0; ks < 2; ++ks) { kf0[ks] = *(const LAS bf16x8*)(kb + koff[ks]); kf1[ks] = *(const LAS bf16x8*)(kb + koff[ks] + 32 * RB); }
;             f32x16 a0, a1;
;             if (DIFF) {
;                 if (j < cq) {
;                     const float base = -slopeL2 * dq - mrun;
; #pragma unroll
;                     for (int r = 0; r < 16; ++r) { const float c = (float)((r & 3) + 8 * (r >> 2)); a0[r] = slopeL2 * c + base; a1[r] = slopeL2 * (c + 32.f) + base; }
;                 } else {
; #pragma unroll
;                     for (int r = 0; r < 16; ++r) { const float c = (float)((r & 3) + 8 * (r >> 2)); a0[r] = -slopeL2 * __builtin_fabsf(dq - c) - mrun; a1[r] = -slopeL2 * __builtin_fabsf(dq - (c + 32.f)) - mrun; }
;                 }
;             } else {
;                 if (j <= cq - 3) {
;                     const float t = tab[256] - mrun;
; #pragma unroll
;                     for (int r = 0; r < 16; ++r) { a0[r] = t; a1[r] = t; }
.LBB0_339:
	s_lshl_b32 s19, s61, 14
	s_add_i32 s19, s19, 0
	v_add3_u32 v0, s19, v107, v106
	ds_read_b128 v[94:97], v0
	ds_read_b128 v[86:89], v0 offset:4096
	v_add3_u32 v0, s19, v108, v106
	ds_read_b128 v[90:93], v0
	ds_read_b128 v[82:85], v0 offset:4096
	v_add3_u32 v121, s19, v109, v106
	ds_read_b128 v[124:127], v121
	ds_read_b128 v[128:131], v121 offset:4096
	v_add3_u32 v121, s19, v110, v106
	ds_read_b128 v[132:135], v121
	ds_read_b128 v[136:139], v121 offset:4096
	s_cmp_le_i32 s29, s60
	s_mov_b64 s[24:25], -1
	s_cbranch_scc0 .LBB0_341
	v_readlane_b32 s24, v254, 50
	s_nop 1
	v_mov_b32_e32 v0, s24
	ds_read_b32 v0, v0
	s_mov_b64 s[24:25], 0
	s_waitcnt lgkmcnt(0)
	v_sub_f32_e32 v0, v0, v114
	v_mov_b64_e32 v[64:65], v[14:15]
	v_mov_b64_e32 v[62:63], v[12:13]
	v_mov_b64_e32 v[60:61], v[10:11]
	v_mov_b64_e32 v[58:59], v[8:9]
	v_mov_b64_e32 v[56:57], v[6:7]
	v_mov_b64_e32 v[54:55], v[4:5]
	v_mov_b64_e32 v[52:53], v[2:3]
	v_mov_b64_e32 v[50:51], v[0:1]

; #define LAS __attribute__((address_space(3)))
; __device__ __forceinline__ float x32_max(float v) { float a = v, b = v; swap32(a, b); return fmaxf(a, b); }
; #define MFMA32(a, b, c) __builtin_amdgcn_mfma_f32_32x32x16_bf16((a), (b), (c), 0, 0, 0)
; template <bool DIFF, bool FIXED, bool F32SRC> ...
;     ...
;             for (int ks = 0; ks < 2; ++ks) { a0 = MFMA32(kf0[ks], qf[ks], a0); a1 = MFMA32(kf1[ks], qf[ks], a1); }
;             __builtin_amdgcn_sched_barrier(0);
; #pragma unroll
;             for (int ks = 0; ks < 2; ++ks) { kf0[ks] = *(const LAS bf16x8*)(kb + koff[ks + 2]); kf1[ks] = *(const LAS bf16x8*)(kb + koff[ks + 2] + 32 * RB); }
;             __builtin_amdgcn_sched_barrier(0);
; #pragma unroll
;             for (int ks = 0; ks < 2; ++ks) { a0 = MFMA32(kf0[ks], qf[ks + 2], a0); a1 = MFMA32(kf1[ks], qf[ks + 2], a1); }
;             __builtin_amdgcn_sched_barrier(0);
;             bf16x8 vf[4];
;     ...
;             if (!FIXED) {
;             float mx = fmaxf(fmaxf(a0[0], a1[0]), fmaxf(a0[1], a1[1]));
; #pragma unroll
;             for (int r = 2; r < 16; r += 2) mx = fmaxf(fmaxf(mx, fmaxf(a0[r], a1[r])), fmaxf(a0[r + 1], a1[r + 1]));
;             mx = x32_max(mx);
;             if (__any(mx > 0.f)) {
;                 const float dl = fmaxf(mx, 0.f), al = __builtin_amdgcn_exp2f(-dl);
;                 lrun *= al; mrun += dl;
; #pragma unroll
;                 for (int r = 0; r < 16; ++r) { a0[r] -= dl; a1[r] -= dl; }
; #pragma unroll
;                 for (int db = 0; db < NDB; ++db)
; #pragma unroll
;                     for (int r = 0; r < 16; ++r) o[db][r] *= al;
;             }
.LBB0_343:
	v_mov_b32_e32 v51, v0
	s_waitcnt lgkmcnt(0)
	v_mfma_f32_32x32x16_bf16 v[34:49], v[94:97], v[66:69], v[34:49]
	v_mfma_f32_32x32x16_bf16 v[50:65], v[86:89], v[66:69], v[50:65]
	v_mfma_f32_32x32x16_bf16 v[34:49], v[90:93], v[70:73], v[34:49]
	v_mfma_f32_32x32x16_bf16 v[50:65], v[82:85], v[70:73], v[50:65]
	s_waitcnt lgkmcnt(0)
	v_mfma_f32_32x32x16_bf16 v[34:49], v[124:127], v[74:77], v[34:49]
	v_mfma_f32_32x32x16_bf16 v[50:65], v[128:131], v[74:77], v[50:65]
	v_mfma_f32_32x32x16_bf16 v[34:49], v[132:135], v[78:81], v[34:49]
	v_mfma_f32_32x32x16_bf16 v[50:65], v[136:139], v[78:81], v[50:65]
	v_add_u32_e32 v120, s19, v111
	ds_read_b64_tr_b16 v[162:163], v120 offset:8192
	ds_read_b64_tr_b16 v[164:165], v120 offset:9216
	ds_read_b64_tr_b16 v[166:167], v120 offset:10240
	ds_read_b64_tr_b16 v[168:169], v120 offset:11264
	ds_read_b64_tr_b16 v[170:171], v120 offset:12288
	ds_read_b64_tr_b16 v[172:173], v120 offset:13312
	ds_read_b64_tr_b16 v[174:175], v120 offset:14336
	ds_read_b64_tr_b16 v[176:177], v120 offset:15360
	s_nop 11
	v_max_f32_e32 v0, v51, v51
	v_max_f32_e32 v82, v35, v35
	v_max_f32_e32 v0, v82, v0
	v_max_f32_e32 v82, v52, v52
	v_max_f32_e32 v83, v36, v36
	v_max_f32_e32 v82, v83, v82
	v_max_f32_e32 v83, v53, v53
	v_max_f32_e32 v84, v37, v37
	v_max3_f32 v0, v34, v50, v0
	v_max_f32_e32 v83, v84, v83
	v_max3_f32 v0, v0, v82, v83
	v_max_f32_e32 v82, v54, v54
	v_max_f32_e32 v83, v38, v38
	v_max_f32_e32 v82, v83, v82
	v_max_f32_e32 v83, v55, v55
	v_max_f32_e32 v84, v39, v39
	v_max_f32_e32 v83, v84, v83
	v_max3_f32 v0, v0, v82, v83
	v_max_f32_e32 v82, v56, v56
	v_max_f32_e32 v83, v40, v40
	v_max_f32_e32 v82, v83, v82
	v_max_f32_e32 v83, v57, v57
	v_max_f32_e32 v84, v41, v41
	v_max_f32_e32 v83, v84, v83
	v_max3_f32 v0, v0, v82, v83
	v_max_f32_e32 v82, v58, v58
	v_max_f32_e32 v83, v42, v42
	v_max_f32_e32 v82, v83, v82
	v_max_f32_e32 v83, v59, v59
	v_max_f32_e32 v84, v43, v43
	v_max_f32_e32 v83, v84, v83
	v_max3_f32 v0, v0, v82, v83
	v_max_f32_e32 v82, v60, v60
	v_max_f32_e32 v83, v44, v44
	v_max_f32_e32 v82, v83, v82
	v_max_f32_e32 v83, v61, v61
	v_max_f32_e32 v84, v45, v45
	v_max_f32_e32 v83, v84, v83
	v_max3_f32 v0, v0, v82, v83
	v_max_f32_e32 v82, v62, v62
	v_max_f32_e32 v83, v46, v46
	v_max_f32_e32 v82, v83, v82
	v_max_f32_e32 v83, v63, v63
	v_max_f32_e32 v84, v47, v47
	v_max_f32_e32 v83, v84, v83
	v_max3_f32 v0, v0, v82, v83
	v_max_f32_e32 v82, v64, v64
	v_max_f32_e32 v83, v48, v48
	v_max_f32_e32 v82, v83, v82
	v_max_f32_e32 v83, v65, v65
	v_max_f32_e32 v84, v49, v49
	v_max_f32_e32 v83, v84, v83
	v_max3_f32 v0, v0, v82, v83
	v_mov_b32_e32 v82, v0
	s_nop 1
	v_permlane32_swap_b32 v0, v82
	s_nop 1
	s_nop 0
	v_max_f32_e32 v82, v82, v82
	v_max_f32_e32 v0, v0, v0
	v_max_f32_e32 v0, v0, v82
	v_cmp_lt_f32_e32 vcc, 0, v0
	s_cbranch_vccz .LBB0_345
	v_max_f32_e32 v0, v0, v0
	v_max_f32_e32 v0, 0, v0
	v_exp_f32_e64 v82, -v0
	v_pk_add_f32 v[34:35], v[34:35], v[0:1] op_sel_hi:[1,0] neg_lo:[0,1] neg_hi:[0,1]
	v_pk_add_f32 v[50:51], v[50:51], v[0:1] op_sel_hi:[1,0] neg_lo:[0,1] neg_hi:[0,1]
	v_pk_add_f32 v[36:37], v[36:37], v[0:1] op_sel_hi:[1,0] neg_lo:[0,1] neg_hi:[0,1]
	v_mul_f32_e32 v112, v112, v82
	v_pk_add_f32 v[52:53], v[52:53], v[0:1] op_sel_hi:[1,0] neg_lo:[0,1] neg_hi:[0,1]
	v_pk_add_f32 v[38:39], v[38:39], v[0:1] op_sel_hi:[1,0] neg_lo:[0,1] neg_hi:[0,1]
	v_pk_add_f32 v[54:55], v[54:55], v[0:1] op_sel_hi:[1,0] neg_lo:[0,1] neg_hi:[0,1]
	v_pk_add_f32 v[40:41], v[40:41], v[0:1] op_sel_hi:[1,0] neg_lo:[0,1] neg_hi:[0,1]
	v_pk_add_f32 v[56:57], v[56:57], v[0:1] op_sel_hi:[1,0] neg_lo:[0,1] neg_hi:[0,1]
	v_pk_add_f32 v[42:43], v[42:43], v[0:1] op_sel_hi:[1,0] neg_lo:[0,1] neg_hi:[0,1]
	v_pk_add_f32 v[58:59], v[58:59], v[0:1] op_sel_hi:[1,0] neg_lo:[0,1] neg_hi:[0,1]
	v_pk_add_f32 v[44:45], v[44:45], v[0:1] op_sel_hi:[1,0] neg_lo:[0,1] neg_hi:[0,1]
	v_pk_add_f32 v[60:61], v[60:61], v[0:1] op_sel_hi:[1,0] neg_lo:[0,1] neg_hi:[0,1]
	v_pk_add_f32 v[46:47], v[46:47], v[0:1] op_sel_hi:[1,0] neg_lo:[0,1] neg_hi:[0,1]
	v_pk_add_f32 v[62:63], v[62:63], v[0:1] op_sel_hi:[1,0] neg_lo:[0,1] neg_hi:[0,1]
	v_pk_add_f32 v[48:49], v[48:49], v[0:1] op_sel_hi:[1,0] neg_lo:[0,1] neg_hi:[0,1]
	v_pk_add_f32 v[64:65], v[64:65], v[0:1] op_sel_hi:[1,0] neg_lo:[0,1] neg_hi:[0,1]
	v_pk_mul_f32 v[16:17], v[16:17], v[82:83] op_sel_hi:[1,0]
	v_pk_mul_f32 v[14:15], v[14:15], v[82:83] op_sel_hi:[1,0]
	v_pk_mul_f32 v[12:13], v[12:13], v[82:83] op_sel_hi:[1,0]
	v_pk_mul_f32 v[10:11], v[10:11], v[82:83] op_sel_hi:[1,0]
	v_pk_mul_f32 v[8:9], v[8:9], v[82:83] op_sel_hi:[1,0]
	v_pk_mul_f32 v[6:7], v[6:7], v[82:83] op_sel_hi:[1,0]
	v_pk_mul_f32 v[4:5], v[4:5], v[82:83] op_sel_hi:[1,0]
	v_pk_mul_f32 v[2:3], v[2:3], v[82:83] op_sel_hi:[1,0]
	v_pk_mul_f32 v[32:33], v[32:33], v[82:83] op_sel_hi:[1,0]
	v_pk_mul_f32 v[30:31], v[30:31], v[82:83] op_sel_hi:[1,0]
	v_pk_mul_f32 v[28:29], v[28:29], v[82:83] op_sel_hi:[1,0]
	v_pk_mul_f32 v[26:27], v[26:27], v[82:83] op_sel_hi:[1,0]
	v_pk_mul_f32 v[24:25], v[24:25], v[82:83] op_sel_hi:[1,0]
	v_pk_mul_f32 v[22:23], v[22:23], v[82:83] op_sel_hi:[1,0]
	v_pk_mul_f32 v[20:21], v[20:21], v[82:83] op_sel_hi:[1,0]
	v_pk_mul_f32 v[18:19], v[18:19], v[82:83] op_sel_hi:[1,0]
	v_add_f32_e32 v114, v114, v0
